# seam 12->13 replaced by a 96-workgroup Y-producer counter handoff (attention workgroups run through)
# baseline (speedup 1.0000x reference)
.LBB0_924:
	s_cmpk_lg_i32 s56, 0x100
	s_cbranch_scc1 .Lq_nosig
	s_cmp_gt_i32 s41, 13
	s_cbranch_scc0 .Lq_nosig
	s_cmpk_gt_i32 s2, 0x5f
	s_cbranch_scc1 .Lq_nosig
	s_cmp_lg_u32 s94, 0
	s_cbranch_scc1 .Lq_nosig
	s_add_u32 s0, s54, 0xd603f00
	s_addc_u32 s1, s55, 0
	s_mov_b64 exec, 1
	buffer_wbl2 sc1
	s_waitcnt vmcnt(0)
	v_mov_b32_e32 v0, 0
	v_mov_b32_e32 v1, 1
	global_atomic_add v0, v1, s[0:1]
	s_waitcnt vmcnt(0)
	s_mov_b64 exec, -1

.LBB0_1368:
	s_cmp_gt_i32 s41, 13
	s_cselect_b64 s[0:1], -1, 0
	s_and_b64 s[4:5], s[0:1], s[62:63]
	s_andn2_b64 vcc, exec, s[4:5]
	s_cbranch_vccnz .LBB0_1418
	s_cmpk_lg_i32 s56, 0x100
	s_cbranch_scc1 .Lq_seam
	s_cmpk_gt_i32 s2, 0x5f
	s_cbranch_scc1 .Lq_wdone
	s_cmp_lg_u32 s94, 0
	s_cbranch_scc1 .Lq_wdone
	s_add_u32 s4, s54, 0xd603f00
	s_addc_u32 s5, s55, 0
	v_mov_b32_e32 v0, 0
	s_mov_b32 s3, 0
.Lq_poll:
	global_load_dword v1, v0, s[4:5] sc1
	s_waitcnt vmcnt(0)
	v_readfirstlane_b32 s6, v1
	s_cmpk_ge_u32 s6, 0x60
	s_cbranch_scc1 .Lq_pdone
	s_sleep 1
	s_add_i32 s3, s3, 1
	s_cmp_lt_u32 s3, 0x40000
	s_cbranch_scc1 .Lq_poll
.Lq_pdone:
	buffer_inv sc1
	s_waitcnt vmcnt(0)
.Lq_wdone:
	s_waitcnt vmcnt(0) lgkmcnt(0)
	s_barrier
	s_branch .LBB0_1418
.Lq_seam:
	s_waitcnt vmcnt(0)
	s_waitcnt vmcnt(0)
	s_barrier
	s_mov_b64 s[4:5], exec
	v_readlane_b32 s6, v246, 0
	v_readlane_b32 s7, v246, 1
	s_and_b64 s[6:7], s[4:5], s[6:7]
	s_mov_b64 exec, s[6:7]
	s_cbranch_execz .LBB0_1417
	s_add_i32 s3, 0, 0x20000
	v_mov_b32_e32 v0, s3
	s_waitcnt vmcnt(0) expcnt(0) lgkmcnt(0)
	ds_read_b32 v2, v0
	s_add_i32 s3, 0, 0x20004
	v_mov_b32_e32 v0, s3
	ds_read_b32 v0, v0
	s_waitcnt lgkmcnt(1)
	v_cmp_ne_u32_e32 vcc, 0, v2
	s_cbranch_vccnz .LBB0_1385
	s_add_u32 s6, s54, 0xd600200
	s_addc_u32 s7, s55, 0
	s_add_u32 s8, s54, 0xd600400
	s_addc_u32 s9, s55, 0
	s_add_u32 s10, s54, 0xd600500
	s_addc_u32 s11, s55, 0
	s_add_u32 s12, s54, 0xd600600
	s_addc_u32 s13, s55, 0
	s_add_u32 s14, s54, 0xd600700
	s_addc_u32 s15, s55, 0
	s_add_u32 s16, s54, 0xd600800
	s_addc_u32 s17, s55, 0
	s_add_u32 s18, s54, 0xd600900
	s_addc_u32 s19, s55, 0
	s_add_u32 s20, s54, 0xd600a00
	s_addc_u32 s21, s55, 0
	s_add_u32 s22, s54, 0xd600b00
	s_addc_u32 s23, s55, 0
	s_add_u32 s62, s54, 0xd600c00
	s_addc_u32 s63, s55, 0
	s_add_u32 s64, s54, 0xd600d00
	s_addc_u32 s65, s55, 0
	s_add_u32 s66, s54, 0xd600e00
	s_addc_u32 s67, s55, 0
	s_add_u32 s68, s54, 0xd600f00
	s_addc_u32 s69, s55, 0
	s_add_u32 s70, s54, 0xd601000
	s_addc_u32 s71, s55, 0
	s_add_u32 s72, s54, 0xd601100
	s_addc_u32 s73, s55, 0
	s_add_u32 s74, s54, 0xd601200
	v_readlane_b32 s3, v246, 2
	s_addc_u32 s75, s55, 0
	s_mul_i32 s3, s57, s3
	s_add_u32 s76, s54, 0xd601300
	s_mul_i32 s3, s3, s56
	s_addc_u32 s77, s55, 0
	s_mov_b32 s24, 1
	v_mov_b32_e32 v16, 0
	s_branch .LBB0_1373
